# P2 attention softmax: row max / row sum lane^16, lane^32 steps via permlane swaps instead of ds_bpermute round trips
# speedup vs baseline: 1.0022x; 1.0022x over previous
.Lmask_join:
	v_max3_f32 v81, v82, v114, v2
	v_or_b32_e32 v82, s67, v103
	v_cmp_lt_i32_e32 vcc, s68, v82
	s_or_b64 s[16:17], s[0:1], vcc
	v_cmp_le_i32_e32 vcc, v82, v44
	s_and_b64 vcc, s[16:17], vcc
	v_or_b32_e32 v116, v103, v116
	v_cndmask_b32_e32 v108, v96, v40, vcc
	v_cmp_lt_i32_e32 vcc, s69, v82
	s_or_b64 s[16:17], s[0:1], vcc
	v_cmp_lt_i32_e32 vcc, v82, v44
	s_and_b64 vcc, s[16:17], vcc
	v_mul_u32_u24_e32 v116, 0x90, v116
	v_cndmask_b32_e32 v109, v96, v41, vcc
	v_or_b32_e32 v41, 2, v82
	v_cmp_lt_i32_e32 vcc, s68, v41
	s_or_b64 s[16:17], s[0:1], vcc
	v_cmp_le_i32_e32 vcc, v41, v44
	s_and_b64 vcc, s[16:17], vcc
	v_or_b32_e32 v41, 3, v82
	v_cndmask_b32_e32 v110, v96, v42, vcc
	v_cmp_lt_i32_e32 vcc, s68, v41
	s_or_b64 s[0:1], s[0:1], vcc
	v_cmp_le_i32_e32 vcc, v41, v44
	v_and_b32_e32 v42, 64, v95
	s_and_b64 vcc, s[0:1], vcc
	v_xor_b32_e32 v41, 16, v95
	v_add_u32_e32 v42, 64, v42
	v_cndmask_b32_e32 v111, v96, v43, vcc
	v_cmp_lt_i32_e32 vcc, v41, v42
	v_max3_f32 v40, v81, v108, v109
	v_max3_f32 v40, v40, v110, v111
	v_cndmask_b32_e32 v41, v95, v41, vcc
	v_lshlrev_b32_e32 v105, 2, v41
	v_mov_b32_e32 v41, v40
	s_nop 1
	v_permlane16_swap_b32_e32 v40, v41
	s_or_b32 s0, s14, s50
	v_add3_u32 v104, 0, v116, v104
	s_mulk_i32 s13, 0x90
	s_mulk_i32 s0, 0x90
	s_waitcnt lgkmcnt(0)
	v_max_f32_e32 v41, v41, v41
	v_max_f32_e32 v40, v40, v41
	v_xor_b32_e32 v41, 32, v95
	v_cmp_lt_i32_e32 vcc, v41, v42
	s_mulk_i32 s11, 0x90
	s_mulk_i32 s9, 0x90
	v_cndmask_b32_e32 v41, v95, v41, vcc
	v_lshlrev_b32_e32 v106, 2, v41
	v_mov_b32_e32 v41, v40
	s_nop 1
	v_permlane32_swap_b32_e32 v40, v41
	s_mulk_i32 s7, 0x90
	s_mulk_i32 s6, 0x90
	s_waitcnt lgkmcnt(0)
	v_max_f32_e32 v41, v41, v41
	v_max_f32_e32 v40, v40, v41
	v_mul_f32_e32 v40, 0x3e38aa3b, v40
	v_max_f32_e32 v41, v53, v53
	v_max_f32_e32 v107, v40, v41
	v_fma_f32 v42, v74, s70, -v107
	v_fma_f32 v1, v1, s70, -v107
	v_exp_f32_e32 v82, v42
	v_fma_f32 v42, v75, s70, -v107
	v_exp_f32_e32 v88, v1
	v_fma_f32 v1, v47, s70, -v107
	v_exp_f32_e32 v83, v42
	v_fma_f32 v42, v76, s70, -v107
	v_exp_f32_e32 v89, v1
	v_exp_f32_e32 v84, v42
	v_fma_f32 v42, v46, s70, -v107
	v_fma_f32 v43, v80, s70, -v107
	v_exp_f32_e32 v85, v42
	v_exp_f32_e32 v80, v43
	v_fma_f32 v43, v77, s70, -v107
	v_exp_f32_e32 v81, v43
	v_fma_f32 v0, v0, s70, -v107
	v_exp_f32_e32 v87, v0
	v_pk_add_f32 v[0:1], v[88:89], 0 op_sel_hi:[1,0]
	v_fma_f32 v42, v78, s70, -v107
	v_exp_f32_e32 v74, v42
	v_fma_f32 v42, v79, s70, -v107
	v_pk_add_f32 v[0:1], v[84:85], v[0:1]
	v_exp_f32_e32 v75, v42
	v_pk_add_f32 v[42:43], v[80:81], v[0:1]
	v_fma_f32 v0, v90, s70, -v107
	v_exp_f32_e32 v76, v0
	v_fma_f32 v0, v91, s70, -v107
	v_exp_f32_e32 v77, v0
	v_fma_f32 v0, v122, s70, -v107
	v_exp_f32_e32 v78, v0
	v_fma_f32 v0, v123, s70, -v107
	v_fma_f32 v40, v45, s70, -v107
	v_exp_f32_e32 v79, v0
	v_fma_f32 v44, v126, s70, -v107
	v_fma_f32 v45, v127, s70, -v107
	v_exp_f32_e32 v44, v44
	v_exp_f32_e32 v45, v45
	v_exp_f32_e32 v86, v40
	v_pk_add_f32 v[42:43], v[78:79], v[42:43]
	v_fma_f32 v0, v124, s70, -v107
	v_fma_f32 v1, v125, s70, -v107
	v_pk_add_f32 v[46:47], v[44:45], v[42:43]
	v_fma_f32 v42, v130, s70, -v107
	v_add_u32_e32 v126, s13, v104
	v_add_u32_e32 v130, s0, v104
	v_pk_add_f32 v[40:41], v[86:87], 0 op_sel_hi:[1,0]
	v_exp_f32_e32 v0, v0
	v_exp_f32_e32 v1, v1
	ds_read_b64_tr_b16 v[116:117], v126 offset:36864
	ds_read_b64_tr_b16 v[118:119], v130 offset:36864
	v_pk_add_f32 v[40:41], v[82:83], v[40:41]
	v_fma_f32 v43, v131, s70, -v107
	v_pk_add_f32 v[40:41], v[74:75], v[40:41]
	s_or_b32 s0, s12, s51
	v_pk_add_f32 v[40:41], v[76:77], v[40:41]
	s_mulk_i32 s0, 0x90
	v_pk_add_f32 v[90:91], v[0:1], v[40:41]
	v_fma_f32 v40, v128, s70, -v107
	v_fma_f32 v41, v129, s70, -v107
	ds_read_b64_tr_b16 v[122:123], v130 offset:36896
	ds_read_b64_tr_b16 v[120:121], v126 offset:36896
	ds_read_b64_tr_b16 v[124:125], v126 offset:36928
	ds_read_b64_tr_b16 v[128:129], v126 offset:36960
	ds_read_b64_tr_b16 v[126:127], v130 offset:36928
	ds_read_b64_tr_b16 v[130:131], v130 offset:36960
	v_cvt_pk_bf16_f32 v86, v86, v87
	v_cvt_pk_bf16_f32 v87, v88, v89
	v_cvt_pk_bf16_f32 v88, v82, v83
	v_cvt_pk_bf16_f32 v89, v84, v85
	v_fma_f32 v83, v115, s70, -v107
	v_add_u32_e32 v115, s11, v104
	v_add_u32_e32 v138, s0, v104
	s_waitcnt lgkmcnt(6)
	v_mfma_f32_16x16x32_bf16 v[116:119], v[116:119], v[86:89], 0
	v_fma_f32 v82, v132, s70, -v107
	v_fma_f32 v84, v133, s70, -v107
	v_fma_f32 v85, v134, s70, -v107
	s_waitcnt lgkmcnt(4)
	v_mfma_f32_16x16x32_bf16 v[120:123], v[120:123], v[86:89], 0
	v_cvt_pk_bf16_f32 v74, v74, v75
	v_cvt_pk_bf16_f32 v75, v80, v81
	v_cvt_pk_bf16_f32 v76, v76, v77
	s_waitcnt lgkmcnt(1)
	v_mfma_f32_16x16x32_bf16 v[124:127], v[124:127], v[86:89], 0
	v_cvt_pk_bf16_f32 v77, v78, v79
	v_fma_f32 v112, v112, s70, -v107
	s_or_b32 s0, s10, s33
	s_waitcnt lgkmcnt(0)
	v_mfma_f32_16x16x32_bf16 v[86:89], v[128:131], v[86:89], 0
	ds_read_b64_tr_b16 v[128:129], v115 offset:36864
	ds_read_b64_tr_b16 v[130:131], v138 offset:36864
	ds_read_b64_tr_b16 v[80:81], v138 offset:36896
	ds_read_b64_tr_b16 v[78:79], v115 offset:36896
	ds_read_b64_tr_b16 v[132:133], v115 offset:36928
	ds_read_b64_tr_b16 v[136:137], v115 offset:36960
	ds_read_b64_tr_b16 v[134:135], v138 offset:36928
	ds_read_b64_tr_b16 v[138:139], v138 offset:36960
	v_exp_f32_e32 v140, v112
	v_fma_f32 v112, v113, s70, -v107
	s_mulk_i32 s0, 0x90
	s_waitcnt lgkmcnt(6)
	v_mfma_f32_16x16x32_bf16 v[116:119], v[128:131], v[74:77], v[116:119]
	v_exp_f32_e32 v141, v112
	v_fma_f32 v112, v114, s70, -v107
	v_exp_f32_e32 v40, v40
	s_waitcnt lgkmcnt(4)
	v_mfma_f32_16x16x32_bf16 v[78:81], v[78:81], v[74:77], v[120:123]
	v_exp_f32_e32 v41, v41
	v_exp_f32_e32 v42, v42
	v_exp_f32_e32 v43, v43
	s_waitcnt lgkmcnt(1)
	v_mfma_f32_16x16x32_bf16 v[120:123], v[132:135], v[74:77], v[124:127]
	v_exp_f32_e32 v132, v112
	v_exp_f32_e32 v82, v82
	v_exp_f32_e32 v83, v83
	s_waitcnt lgkmcnt(0)
	v_mfma_f32_16x16x32_bf16 v[74:77], v[136:139], v[74:77], v[86:89]
	v_add_f32_e64 v90, v40, v90
	v_add_f32_e64 v91, v41, v91
	v_pk_add_f32 v[46:47], v[42:43], v[46:47]
	v_exp_f32_e32 v84, v84
	v_cvt_pk_bf16_f32 v86, v0, v1
	v_add_u32_e32 v0, s9, v104
	v_add_u32_e32 v1, s0, v104
	ds_read_b64_tr_b16 v[112:113], v0 offset:36864
	ds_read_b64_tr_b16 v[114:115], v1 offset:36864
	v_cvt_pk_bf16_f32 v88, v40, v41
	v_cvt_pk_bf16_f32 v89, v42, v43
	ds_read_b64_tr_b16 v[42:43], v1 offset:36896
	ds_read_b64_tr_b16 v[40:41], v0 offset:36896
	ds_read_b64_tr_b16 v[124:125], v0 offset:36928
	ds_read_b64_tr_b16 v[128:129], v0 offset:36960
	ds_read_b64_tr_b16 v[126:127], v1 offset:36928
	ds_read_b64_tr_b16 v[130:131], v1 offset:36960
	s_or_b32 s0, s8, s35
	v_exp_f32_e32 v85, v85
	v_pk_add_f32 v[90:91], v[82:83], v[90:91]
	v_cvt_pk_bf16_f32 v87, v44, v45
	v_fma_f32 v0, v2, s70, -v107
	v_fma_f32 v2, v108, s70, -v107
	v_fma_f32 v44, v110, s70, -v107
	s_mulk_i32 s0, 0x90
	v_exp_f32_e32 v133, v0
	v_pk_add_f32 v[0:1], v[140:141], v[90:91]
	s_waitcnt lgkmcnt(4)
	v_mfma_f32_16x16x32_bf16 v[40:43], v[40:43], v[86:89], v[78:81]
	v_exp_f32_e32 v90, v2
	v_fma_f32 v2, v109, s70, -v107
	v_add_u32_e32 v45, s7, v104
	s_waitcnt lgkmcnt(1)
	v_mfma_f32_16x16x32_bf16 v[78:81], v[124:127], v[86:89], v[120:123]
	v_exp_f32_e32 v124, v44
	v_fma_f32 v44, v111, s70, -v107
	v_add_u32_e32 v91, s0, v104
	v_mfma_f32_16x16x32_bf16 v[112:115], v[112:115], v[86:89], v[116:119]
	v_exp_f32_e32 v125, v44
	v_pk_add_f32 v[46:47], v[84:85], v[46:47]
	s_and_b64 s[0:1], s[52:53], exec
	s_waitcnt lgkmcnt(0)
	v_mfma_f32_16x16x32_bf16 v[74:77], v[128:131], v[86:89], v[74:77]
	ds_read_b64_tr_b16 v[86:87], v45 offset:36864
	ds_read_b64_tr_b16 v[88:89], v91 offset:36864
	ds_read_b64_tr_b16 v[110:111], v91 offset:36896
	ds_read_b64_tr_b16 v[108:109], v45 offset:36896
	ds_read_b64_tr_b16 v[116:117], v45 offset:36928
	ds_read_b64_tr_b16 v[120:121], v45 offset:36960
	ds_read_b64_tr_b16 v[118:119], v91 offset:36928
	ds_read_b64_tr_b16 v[122:123], v91 offset:36960
	v_exp_f32_e32 v91, v2
	v_cvt_pk_bf16_f32 v82, v82, v83
	v_cvt_pk_bf16_f32 v83, v84, v85
	v_cvt_pk_bf16_f32 v84, v140, v141
	v_cvt_pk_bf16_f32 v85, v132, v133
	v_pk_add_f32 v[44:45], v[132:133], v[46:47]
	s_cselect_b32 s0, s96, s41
	s_waitcnt lgkmcnt(4)
	v_mfma_f32_16x16x32_bf16 v[40:43], v[108:111], v[82:85], v[40:43]
	v_add_f32_e64 v108, v124, v44
	v_add_f32_e64 v109, v125, v45
	v_pk_add_f32 v[0:1], v[90:91], v[0:1]
	s_lshl_b32 s0, s0, 7
	v_pk_mov_b32 v[110:111], v[0:1], v[108:109] op_sel:[1,0]
	v_mov_b32_e32 v1, v109
	s_or_b32 s0, s0, s75
	v_pk_add_f32 v[0:1], v[110:111], v[0:1]
	s_mulk_i32 s0, 0x90
	s_waitcnt lgkmcnt(1)
	v_mfma_f32_16x16x32_bf16 v[44:47], v[116:119], v[82:85], v[78:81]
	v_add_f32_e32 v116, v0, v1
	v_cvt_pk_bf16_f32 v0, v90, v91
	v_add_u32_e32 v90, s6, v104
	v_add_u32_e32 v91, s0, v104
	ds_read_b64_tr_b16 v[78:79], v90 offset:36864
	ds_read_b64_tr_b16 v[80:81], v91 offset:36864
	v_mfma_f32_16x16x32_bf16 v[86:89], v[86:89], v[82:85], v[112:115]
	v_cvt_pk_bf16_f32 v1, v124, v125
	v_mov_b32_e32 v2, v3
	s_waitcnt vmcnt(0)
	v_permlane16_swap_b32_e32 v238, v240
	v_permlane16_swap_b32_e32 v239, v241
	v_permlane16_swap_b32_e32 v242, v244
	v_permlane16_swap_b32_e32 v243, v245
	v_permlane16_swap_b32_e32 v246, v248
	v_permlane16_swap_b32_e32 v247, v249
	v_permlane16_swap_b32_e32 v250, v252
	v_permlane16_swap_b32_e32 v251, v253
	v_permlane16_swap_b32_e32 v154, v156
	v_permlane16_swap_b32_e32 v155, v157
	v_permlane16_swap_b32_e32 v216, v218
	v_permlane16_swap_b32_e32 v217, v219
	v_mov_b64_e32 v[68:69], v[238:239]
	v_mov_b64_e32 v[62:63], v[240:241]
	v_mov_b64_e32 v[56:57], v[242:243]
	v_mov_b64_e32 v[48:49], v[244:245]
	v_mov_b64_e32 v[70:71], v[246:247]
	v_mov_b64_e32 v[64:65], v[248:249]
	v_mov_b64_e32 v[58:59], v[250:251]
	v_mov_b64_e32 v[50:51], v[252:253]
	v_mov_b64_e32 v[72:73], v[154:155]
	v_mov_b64_e32 v[66:67], v[156:157]
	v_mov_b64_e32 v[60:61], v[216:217]
	v_mov_b64_e32 v[54:55], v[218:219]
	v_and_b32_e32 v104, 0xffff0000, v70
	s_waitcnt lgkmcnt(2)
	v_mfma_f32_16x16x32_bf16 v[74:77], v[120:123], v[82:85], v[74:77]
	ds_read_b64_tr_b16 v[84:85], v91 offset:36896
	ds_read_b64_tr_b16 v[82:83], v90 offset:36896
	ds_read_b64_tr_b16 v[108:109], v90 offset:36928
	ds_read_b64_tr_b16 v[112:113], v90 offset:36960
	ds_read_b64_tr_b16 v[110:111], v91 offset:36928
	ds_read_b64_tr_b16 v[114:115], v91 offset:36960
	v_lshlrev_b32_e32 v90, 16, v70
	v_mul_f32_e32 v90, 0xbfb8aa3b, v90
	s_waitcnt lgkmcnt(6)
	v_mfma_f32_16x16x32_bf16 v[78:81], v[78:81], v[0:3], v[86:89]
	v_exp_f32_e32 v90, v90
	s_add_i32 s40, s40, 1
	s_nop 0
	v_mov_b32_e32 v158, v116
	s_nop 1
	v_permlane16_swap_b32_e32 v116, v158
	s_waitcnt lgkmcnt(4)
	v_mfma_f32_16x16x32_bf16 v[82:85], v[82:85], v[0:3], v[40:43]
	v_lshlrev_b32_e32 v88, 16, v73
	v_and_b32_e32 v89, 0xffff0000, v73
	v_lshlrev_b32_e32 v105, 16, v71
	s_waitcnt lgkmcnt(0)
	v_add_f32_e32 v40, v116, v158
	v_mov_b32_e32 v41, v40
	s_nop 1
	v_permlane32_swap_b32_e32 v40, v41
	v_sub_f32_e32 v42, v53, v107
	v_exp_f32_e32 v42, v42
	v_mfma_f32_16x16x32_bf16 v[44:47], v[108:111], v[0:3], v[44:47]
	v_and_b32_e32 v106, 0xffff0000, v69
	s_waitcnt lgkmcnt(0)
	v_add_f32_e32 v40, v40, v41
	v_add_f32_e32 v86, v42, v40
	v_mfma_f32_16x16x32_bf16 v[40:43], v[112:115], v[0:3], v[74:77]
	v_lshl_add_u32 v1, v103, 2, v102
	v_lshlrev_b32_e32 v2, 16, v68
	v_lshlrev_b32_e32 v102, 16, v69
	v_add_u32_e32 v74, s38, v101
	s_mov_b32 s100, 0x9f57000
	v_lshl_add_u64 v[22:23], v[20:21], 0, s[100:101]
	global_load_dwordx4 v[28:31], v[22:23], off offset:3072
	v_and_b32_e32 v101, 0xffff0000, v68
	v_lshlrev_b32_e32 v68, 16, v72
	v_and_b32_e32 v69, 0xffff0000, v72
	v_pk_mul_f32 v[72:73], v[68:69], v[68:69]
	v_mul_f32_e32 v2, 0xbfb8aa3b, v2
	v_fmamk_f32 v72, v72, 0xbdd2d3e7, v93
	v_mul_f32_e32 v72, v72, v68
	v_exp_f32_e32 v2, v2
	v_exp_f32_e32 v91, v72
	v_mul_f32_e32 v72, 0xbfb8aa3b, v101
	v_fmamk_f32 v73, v73, 0xbdd2d3e7, v93
	v_and_b32_e32 v107, 0xffff0000, v71
	v_pk_mul_f32 v[70:71], v[88:89], v[88:89]
	v_exp_f32_e32 v101, v72
	v_mul_f32_e32 v72, 0xbfb8aa3b, v104
	v_mul_f32_e32 v73, v73, v69
	v_exp_f32_e32 v72, v72
	v_exp_f32_e32 v73, v73
	v_fmamk_f32 v70, v70, 0xbdd2d3e7, v93
	v_mul_f32_e32 v102, 0xbfb8aa3b, v102
	v_mul_f32_e32 v104, 0xbfb8aa3b, v105
	v_mul_f32_e32 v70, v70, v88
	v_exp_f32_e32 v102, v102
	v_exp_f32_e32 v104, v104
	v_exp_f32_e32 v105, v70
	v_mul_f32_e32 v70, 0xbfb8aa3b, v106
	v_fmamk_f32 v71, v71, 0xbdd2d3e7, v93
	v_add_f32_e32 v2, 1.0, v2
	v_pk_add_f32 v[90:91], v[90:91], 1.0 op_sel_hi:[1,0]
	v_exp_f32_e32 v109, v70
	v_mul_f32_e32 v70, 0xbfb8aa3b, v107
	v_mul_f32_e32 v71, v71, v89
	v_rcp_f32_e32 v106, v2
	v_mul_f32_e32 v2, v90, v91
	v_exp_f32_e32 v70, v70
	v_exp_f32_e32 v71, v71
	v_rcp_f32_e32 v90, v2
	v_add_f32_e32 v2, 1.0, v101
	v_pk_add_f32 v[72:73], v[72:73], 1.0 op_sel_hi:[1,0]
	v_rcp_f32_e32 v107, v2
	v_mul_f32_e32 v2, v72, v73
	v_ashrrev_i32_e32 v75, 31, v74
	v_rcp_f32_e32 v91, v2
	v_add_f32_e32 v2, 1.0, v102
	v_pk_add_f32 v[72:73], v[104:105], 1.0 op_sel_hi:[1,0]
	v_lshlrev_b64 v[74:75], 11, v[74:75]
	v_rcp_f32_e32 v108, v2
	v_mul_f32_e32 v2, v72, v73
	v_rcp_f32_e32 v0, v86
	v_lshl_add_u64 v[86:87], s[44:45], 0, v[74:75]
	ds_read_b128 v[74:77], v1
	v_rcp_f32_e32 v104, v2
	v_add_f32_e32 v2, 1.0, v109
	v_pk_add_f32 v[70:71], v[70:71], 1.0 op_sel_hi:[1,0]
	v_rcp_f32_e32 v109, v2
	v_mul_f32_e32 v2, v70, v71
	v_rcp_f32_e32 v105, v2
	ds_read_b128 v[70:73], v1 offset:64
	s_waitcnt lgkmcnt(1)
	v_pk_mul_f32 v[76:77], v[76:77], v[88:89]
	v_pk_mul_f32 v[68:69], v[74:75], v[68:69]
	v_pk_mul_f32 v[80:81], v[0:1], v[80:81] op_sel_hi:[0,1]
	v_pk_mul_f32 v[78:79], v[0:1], v[78:79] op_sel_hi:[0,1]
	v_pk_mul_f32 v[68:69], v[90:91], v[68:69]
	v_pk_mul_f32 v[74:75], v[104:105], v[76:77]
	v_pk_fma_f32 v[68:69], v[106:107], v[78:79], v[68:69]
	v_pk_fma_f32 v[74:75], v[108:109], v[80:81], v[74:75]
	v_lshlrev_b32_e32 v2, 1, v103
	v_cvt_pk_bf16_f32 v76, v68, v69
	v_cvt_pk_bf16_f32 v77, v74, v75
	v_lshl_add_u64 v[68:69], v[86:87], 0, v[2:3]
	v_bfe_u32 v158, v52, 4, 1
	v_mul_u32_u24_e32 v158, 24, v158
	v_mov_b32_e32 v159, 0
	v_lshl_add_u64 v[158:159], v[68:69], 0, v[158:159]
	v_mov_b64_e32 v[238:239], v[76:77]
	v_pk_mul_f32 v[74:75], v[0:1], v[84:85] op_sel_hi:[0,1]
	v_pk_mul_f32 v[76:77], v[0:1], v[82:83] op_sel_hi:[0,1]
	v_lshlrev_b32_e32 v2, 16, v62
	v_and_b32_e32 v82, 0xffff0000, v62
	v_lshlrev_b32_e32 v83, 16, v63
	v_and_b32_e32 v84, 0xffff0000, v63
	v_lshlrev_b32_e32 v62, 16, v66
	v_and_b32_e32 v63, 0xffff0000, v66
	v_pk_mul_f32 v[78:79], v[62:63], v[62:63]
	v_lshlrev_b32_e32 v80, 16, v64
	v_fmamk_f32 v78, v78, 0xbdd2d3e7, v93
	v_mul_f32_e32 v2, 0xbfb8aa3b, v2
	v_mul_f32_e32 v80, 0xbfb8aa3b, v80
	v_mul_f32_e32 v78, v78, v62
	v_and_b32_e32 v85, 0xffff0000, v64
	v_lshlrev_b32_e32 v86, 16, v65
	v_and_b32_e32 v87, 0xffff0000, v65
	s_mov_b32 s100, 0x9f5a000
	v_lshl_add_u64 v[24:25], v[20:21], 0, s[100:101]
	global_load_dwordx4 v[24:27], v[24:25], off offset:2048
	v_lshlrev_b32_e32 v64, 16, v67
	v_and_b32_e32 v65, 0xffff0000, v67
	v_exp_f32_e32 v2, v2
	v_exp_f32_e32 v80, v80
	v_exp_f32_e32 v81, v78
	v_mul_f32_e32 v78, 0xbfb8aa3b, v82
	v_fmamk_f32 v79, v79, 0xbdd2d3e7, v93
	v_pk_mul_f32 v[66:67], v[64:65], v[64:65]
	v_exp_f32_e32 v88, v78
	v_mul_f32_e32 v78, 0xbfb8aa3b, v85
	v_mul_f32_e32 v79, v79, v63
	v_exp_f32_e32 v78, v78
	v_exp_f32_e32 v79, v79
	v_mul_f32_e32 v82, 0xbfb8aa3b, v83
	v_fmamk_f32 v66, v66, 0xbdd2d3e7, v93
	v_exp_f32_e32 v89, v82
	v_mul_f32_e32 v82, 0xbfb8aa3b, v86
	v_mul_f32_e32 v66, v66, v64
	v_exp_f32_e32 v82, v82
	v_exp_f32_e32 v83, v66
	v_mul_f32_e32 v66, 0xbfb8aa3b, v84
	v_fmamk_f32 v67, v67, 0xbdd2d3e7, v93
	v_add_f32_e32 v2, 1.0, v2
	v_pk_add_f32 v[80:81], v[80:81], 1.0 op_sel_hi:[1,0]
	v_exp_f32_e32 v86, v66
	v_mul_f32_e32 v66, 0xbfb8aa3b, v87
	v_mul_f32_e32 v67, v67, v65
	v_rcp_f32_e32 v84, v2
	v_mul_f32_e32 v2, v80, v81
	v_exp_f32_e32 v66, v66
	v_exp_f32_e32 v67, v67
	v_rcp_f32_e32 v80, v2
	v_add_f32_e32 v2, 1.0, v88
	v_pk_add_f32 v[78:79], v[78:79], 1.0 op_sel_hi:[1,0]
	v_rcp_f32_e32 v85, v2
	v_mul_f32_e32 v2, v78, v79
	v_rcp_f32_e32 v81, v2
	v_add_f32_e32 v2, 1.0, v89
	v_pk_add_f32 v[82:83], v[82:83], 1.0 op_sel_hi:[1,0]
	v_rcp_f32_e32 v78, v2
	v_mul_f32_e32 v2, v82, v83
	v_rcp_f32_e32 v82, v2
	v_add_f32_e32 v2, 1.0, v86
	v_pk_add_f32 v[66:67], v[66:67], 1.0 op_sel_hi:[1,0]
	v_rcp_f32_e32 v79, v2
	v_mul_f32_e32 v2, v66, v67
	v_rcp_f32_e32 v83, v2
	s_waitcnt lgkmcnt(0)
	v_pk_mul_f32 v[64:65], v[72:73], v[64:65]
	v_lshlrev_b32_e32 v2, 16, v56
	v_and_b32_e32 v72, 0xffff0000, v56
	v_pk_mul_f32 v[64:65], v[82:83], v[64:65]
	v_lshlrev_b32_e32 v73, 16, v57
	v_pk_fma_f32 v[64:65], v[78:79], v[74:75], v[64:65]
	v_and_b32_e32 v74, 0xffff0000, v57
	v_lshlrev_b32_e32 v56, 16, v60
	v_and_b32_e32 v57, 0xffff0000, v60
	v_pk_mul_f32 v[66:67], v[0:1], v[46:47] op_sel_hi:[0,1]
	v_pk_mul_f32 v[46:47], v[56:57], v[56:57]
	v_pk_mul_f32 v[62:63], v[70:71], v[62:63]
	v_lshlrev_b32_e32 v75, 16, v58
	v_fmamk_f32 v46, v46, 0xbdd2d3e7, v93
	v_pk_mul_f32 v[62:63], v[80:81], v[62:63]
	v_mul_f32_e32 v2, 0xbfb8aa3b, v2
	v_mul_f32_e32 v60, 0xbfb8aa3b, v75
	v_mul_f32_e32 v46, v46, v56
	v_pk_fma_f32 v[62:63], v[84:85], v[76:77], v[62:63]
	v_and_b32_e32 v76, 0xffff0000, v58
	v_lshlrev_b32_e32 v77, 16, v59
	v_and_b32_e32 v78, 0xffff0000, v59
	v_lshlrev_b32_e32 v58, 16, v61
	v_and_b32_e32 v59, 0xffff0000, v61
	v_exp_f32_e32 v2, v2
	v_exp_f32_e32 v60, v60
	s_mov_b32 s100, 0x9f5d000
	v_lshl_add_u64 v[22:23], v[20:21], 0, s[100:101]
	global_load_dwordx4 v[36:39], v[22:23], off offset:1024
	v_exp_f32_e32 v61, v46
	v_mul_f32_e32 v46, 0xbfb8aa3b, v72
	v_fmamk_f32 v47, v47, 0xbdd2d3e7, v93
	v_pk_mul_f32 v[70:71], v[0:1], v[44:45] op_sel_hi:[0,1]
	v_pk_mul_f32 v[44:45], v[58:59], v[58:59]
	v_exp_f32_e32 v75, v46
	v_mul_f32_e32 v46, 0xbfb8aa3b, v76
	v_mul_f32_e32 v47, v47, v57
	v_exp_f32_e32 v46, v46
	v_exp_f32_e32 v47, v47
	v_mul_f32_e32 v72, 0xbfb8aa3b, v73
	v_fmamk_f32 v44, v44, 0xbdd2d3e7, v93
	v_exp_f32_e32 v76, v72
	v_mul_f32_e32 v72, 0xbfb8aa3b, v77
	v_mul_f32_e32 v44, v44, v58
	v_exp_f32_e32 v72, v72
	v_exp_f32_e32 v73, v44
	v_mul_f32_e32 v44, 0xbfb8aa3b, v74
	v_fmamk_f32 v45, v45, 0xbdd2d3e7, v93
	v_add_f32_e32 v2, 1.0, v2
	v_pk_add_f32 v[60:61], v[60:61], 1.0 op_sel_hi:[1,0]
	v_exp_f32_e32 v77, v44
	v_mul_f32_e32 v44, 0xbfb8aa3b, v78
	v_mul_f32_e32 v45, v45, v59
	v_rcp_f32_e32 v74, v2
	v_mul_f32_e32 v2, v60, v61
	v_exp_f32_e32 v44, v44
	v_exp_f32_e32 v45, v45
	v_rcp_f32_e32 v60, v2
	v_add_f32_e32 v2, 1.0, v75
	v_pk_add_f32 v[46:47], v[46:47], 1.0 op_sel_hi:[1,0]
	v_rcp_f32_e32 v75, v2
	v_mul_f32_e32 v2, v46, v47
	v_rcp_f32_e32 v61, v2
	v_add_f32_e32 v2, 1.0, v76
	v_pk_add_f32 v[46:47], v[72:73], 1.0 op_sel_hi:[1,0]
	v_cvt_pk_bf16_f32 v62, v62, v63
	v_cvt_pk_bf16_f32 v63, v64, v65
	v_rcp_f32_e32 v76, v2
	v_mul_f32_e32 v2, v46, v47
	v_mov_b64_e32 v[240:241], v[62:63]
	s_nop 1
	v_permlane16_swap_b32_e32 v238, v240
	v_permlane16_swap_b32_e32 v239, v241
	global_store_dwordx4 v[158:159], v[238:241], off
	ds_read_b128 v[62:65], v1 offset:128
	v_rcp_f32_e32 v72, v2
	v_add_f32_e32 v2, 1.0, v77
	v_pk_add_f32 v[44:45], v[44:45], 1.0 op_sel_hi:[1,0]
	v_rcp_f32_e32 v77, v2
	v_mul_f32_e32 v2, v44, v45
	v_rcp_f32_e32 v73, v2
	ds_read_b128 v[44:47], v1 offset:192
	s_waitcnt lgkmcnt(1)
	v_pk_mul_f32 v[58:59], v[64:65], v[58:59]
	v_pk_mul_f32 v[56:57], v[62:63], v[56:57]
	v_pk_mul_f32 v[58:59], v[72:73], v[58:59]
	v_pk_mul_f32 v[56:57], v[60:61], v[56:57]
	v_pk_fma_f32 v[58:59], v[76:77], v[66:67], v[58:59]
	v_pk_fma_f32 v[56:57], v[74:75], v[70:71], v[56:57]
	v_pk_mul_f32 v[42:43], v[0:1], v[42:43] op_sel_hi:[0,1]
	v_pk_mul_f32 v[0:1], v[0:1], v[40:41] op_sel_hi:[0,1]
	v_lshlrev_b32_e32 v40, 16, v54
	s_mov_b32 s100, s66
	v_lshl_add_u64 v[32:33], v[20:21], 0, s[100:101]
	global_load_dwordx4 v[32:35], v[32:33], off
	v_and_b32_e32 v41, 0xffff0000, v54
	v_cvt_pk_bf16_f32 v56, v56, v57
	v_cvt_pk_bf16_f32 v57, v58, v59
	v_lshlrev_b32_e32 v2, 16, v48
	v_and_b32_e32 v58, 0xffff0000, v48
	v_lshlrev_b32_e32 v59, 16, v49
	v_and_b32_e32 v60, 0xffff0000, v49
	v_lshlrev_b32_e32 v48, 16, v55
	v_and_b32_e32 v49, 0xffff0000, v55
	v_pk_mul_f32 v[54:55], v[40:41], v[40:41]
	v_mov_b64_e32 v[242:243], v[56:57]
	v_lshlrev_b32_e32 v56, 16, v50
	v_fmamk_f32 v54, v54, 0xbdd2d3e7, v93
	v_mul_f32_e32 v2, 0xbfb8aa3b, v2
	v_mul_f32_e32 v56, 0xbfb8aa3b, v56
	v_mul_f32_e32 v54, v54, v40
	v_and_b32_e32 v61, 0xffff0000, v50
	v_exp_f32_e32 v2, v2
	v_exp_f32_e32 v56, v56
	v_exp_f32_e32 v57, v54
	v_mul_f32_e32 v54, 0xbfb8aa3b, v58
	v_fmamk_f32 v55, v55, 0xbdd2d3e7, v93
	v_lshlrev_b32_e32 v62, 16, v51
	v_and_b32_e32 v63, 0xffff0000, v51
	v_pk_mul_f32 v[50:51], v[48:49], v[48:49]
	v_exp_f32_e32 v64, v54
	v_mul_f32_e32 v54, 0xbfb8aa3b, v61
	v_mul_f32_e32 v55, v55, v41
	v_exp_f32_e32 v54, v54
	v_exp_f32_e32 v55, v55
	v_mul_f32_e32 v58, 0xbfb8aa3b, v59
	v_fmamk_f32 v50, v50, 0xbdd2d3e7, v93
	v_exp_f32_e32 v65, v58
	v_mul_f32_e32 v58, 0xbfb8aa3b, v62
	v_mul_f32_e32 v50, v50, v48
	v_exp_f32_e32 v58, v58
	v_exp_f32_e32 v59, v50
	v_mul_f32_e32 v50, 0xbfb8aa3b, v60
	v_fmamk_f32 v51, v51, 0xbdd2d3e7, v93
	v_add_f32_e32 v2, 1.0, v2
	v_pk_add_f32 v[56:57], v[56:57], 1.0 op_sel_hi:[1,0]
	v_exp_f32_e32 v62, v50
	v_mul_f32_e32 v50, 0xbfb8aa3b, v63
	v_mul_f32_e32 v51, v51, v49
	v_rcp_f32_e32 v60, v2
	s_mov_b32 s100, 0x9f62000
	v_lshl_add_u64 v[20:21], v[20:21], 0, s[100:101]
	global_load_dwordx4 v[20:23], v[20:21], off offset:3072
	v_mul_f32_e32 v2, v56, v57
	v_exp_f32_e32 v50, v50
	v_exp_f32_e32 v51, v51
	v_rcp_f32_e32 v56, v2
	v_add_f32_e32 v2, 1.0, v64
	v_pk_add_f32 v[54:55], v[54:55], 1.0 op_sel_hi:[1,0]
	v_rcp_f32_e32 v61, v2
	v_mul_f32_e32 v2, v54, v55
	v_rcp_f32_e32 v57, v2
	v_add_f32_e32 v2, 1.0, v65
	v_pk_add_f32 v[58:59], v[58:59], 1.0 op_sel_hi:[1,0]
	v_rcp_f32_e32 v54, v2
	v_mul_f32_e32 v2, v58, v59
	v_rcp_f32_e32 v58, v2
	v_add_f32_e32 v2, 1.0, v62
	v_pk_add_f32 v[50:51], v[50:51], 1.0 op_sel_hi:[1,0]
	v_rcp_f32_e32 v55, v2
	v_mul_f32_e32 v2, v50, v51
	v_rcp_f32_e32 v59, v2
	s_waitcnt lgkmcnt(0)
	v_pk_mul_f32 v[46:47], v[46:47], v[48:49]
	v_pk_mul_f32 v[40:41], v[44:45], v[40:41]
	s_addk_i32 s38, 0x80
	v_pk_mul_f32 v[40:41], v[56:57], v[40:41]
	v_pk_mul_f32 v[44:45], v[58:59], v[46:47]
	v_pk_fma_f32 v[0:1], v[60:61], v[0:1], v[40:41]
	v_pk_fma_f32 v[42:43], v[54:55], v[42:43], v[44:45]
	v_cvt_pk_bf16_f32 v0, v0, v1
	v_cvt_pk_bf16_f32 v1, v42, v43
	v_mov_b64_e32 v[244:245], v[0:1]
	s_nop 1
	v_permlane16_swap_b32_e32 v242, v244
	v_permlane16_swap_b32_e32 v243, v245
	global_store_dwordx4 v[158:159], v[242:245], off offset:64
	s_waitcnt lgkmcnt(0)
	s_barrier
	s_add_u32 s54, s54, 0x160000
	s_addc_u32 s55, s55, 0
	s_cmp_eq_u32 s54, 0x1600000
	s_cbranch_scc1 .LBB0_281
